# baseline (speedup 1.0000x reference)
; __device__ __forceinline__ void phase0(const Params& p, char* smem) {
;     ...
;         for (int k = 0; k < 128; k += 8) {
;           float wv[8];
; #pragma unroll
;           for (int u = 0; u < 8; ++u) wv[u] = wp[(size_t)(k + u) * 6144];
; #pragma unroll
;           for (int b = 0; b < 33; ++b) {
;             float4 s0 = *(const float4*)(scw + b * 128 + k), s1 = *(const float4*)(scw + b * 128 + k + 4);
;             acc[b] += s0.x * wv[0] + s0.y * wv[1] + s0.z * wv[2] + s0.w * wv[3] + s1.x * wv[4] + s1.y * wv[5] + s1.z * wv[6] + s1.w * wv[7];
.LBB0_1949:
	v_add_co_u32_e32 v2, vcc, s63, v56
	global_load_dword v64, v[56:57], off
	s_nop 0
	v_addc_co_u32_e32 v3, vcc, 0, v57, vcc
	global_load_dword v65, v[2:3], off
	v_add_co_u32_e32 v2, vcc, s64, v56
	s_add_i32 s7, s7, 8
	s_nop 0
	v_addc_co_u32_e32 v3, vcc, 0, v57, vcc
	global_load_dword v62, v[2:3], off
	v_add_co_u32_e32 v2, vcc, s65, v56
	s_cmpk_lt_u32 s7, 0x78
	s_nop 0
	v_addc_co_u32_e32 v3, vcc, 0, v57, vcc
	global_load_dword v63, v[2:3], off
	v_add_co_u32_e32 v2, vcc, s66, v56
	v_addc_co_u32_e32 v3, vcc, 0, v57, vcc
	global_load_dword v60, v[2:3], off
	v_add_co_u32_e32 v2, vcc, s67, v56
	v_addc_co_u32_e32 v3, vcc, 0, v57, vcc
	global_load_dword v61, v[2:3], off
	v_add_co_u32_e32 v2, vcc, s68, v56
	v_addc_co_u32_e32 v3, vcc, 0, v57, vcc
	global_load_dword v58, v[2:3], off
	v_add_co_u32_e32 v2, vcc, s69, v56
	s_nop 1
	v_addc_co_u32_e32 v3, vcc, 0, v57, vcc
	global_load_dword v59, v[2:3], off
	s_waitcnt vmcnt(0)
	v_mov_b32_e32 v70, v65
	v_mov_b32_e32 v68, v63
	v_mov_b32_e32 v66, v61
	ds_read_b128 v[2:5], v80
	ds_read_b128 v[6:9], v80 offset:16
	v_lshl_add_u64 v[56:57], v[56:57], 0, s[40:41]
	s_waitcnt lgkmcnt(1)
	v_pk_mul_f32 v[2:3], v[64:65], v[2:3]
	v_pk_mul_f32 v[4:5], v[62:63], v[4:5]
	v_add_f32_e32 v2, v2, v3
	v_add_f32_e32 v2, v2, v4
	s_waitcnt lgkmcnt(0)
	v_pk_mul_f32 v[6:7], v[60:61], v[6:7]
	v_add_f32_e32 v2, v2, v5
	v_add_f32_e32 v2, v2, v6
	v_add_f32_e32 v2, v2, v7
	s_waitcnt vmcnt(0)
	v_pk_mul_f32 v[8:9], v[58:59], v[8:9]
	s_nop 0
	v_add_f32_e32 v2, v2, v8
	v_add_f32_e32 v2, v2, v9
	v_add_f32_e32 v79, v79, v2
	ds_read_b128 v[2:5], v80 offset:512
	ds_read_b128 v[6:9], v80 offset:528
	ds_read_b128 v[10:13], v80 offset:1024
	ds_read_b128 v[82:85], v80 offset:1040
	v_mov_b32_e32 v14, v59
	s_waitcnt lgkmcnt(3)
	v_mov_b32_e32 v87, v2
	s_waitcnt lgkmcnt(1)
	v_mov_b32_e32 v2, v11
	v_mov_b32_e32 v86, v10
	v_pk_mul_f32 v[2:3], v[70:71], v[2:3] op_sel_hi:[0,1]
	v_pk_fma_f32 v[2:3], v[64:65], v[86:87], v[2:3] op_sel_hi:[0,1,1]
	v_mov_b32_e32 v10, v12
	v_mov_b32_e32 v11, v4
	v_pk_fma_f32 v[2:3], v[62:63], v[10:11], v[2:3] op_sel_hi:[0,1,1]
	v_mov_b32_e32 v4, v13
	v_pk_fma_f32 v[2:3], v[68:69], v[4:5], v[2:3] op_sel_hi:[0,1,1]
	s_waitcnt lgkmcnt(0)
	v_mov_b32_e32 v4, v82
	v_mov_b32_e32 v5, v6
	v_pk_fma_f32 v[2:3], v[60:61], v[4:5], v[2:3] op_sel_hi:[0,1,1]
	v_mov_b32_e32 v6, v83
	v_pk_fma_f32 v[2:3], v[66:67], v[6:7], v[2:3] op_sel_hi:[0,1,1]
	v_mov_b32_e32 v4, v84
	v_mov_b32_e32 v5, v8
	v_pk_fma_f32 v[2:3], v[58:59], v[4:5], v[2:3] op_sel_hi:[0,1,1]
	v_mov_b32_e32 v8, v85
	v_pk_fma_f32 v[2:3], v[14:15], v[8:9], v[2:3] op_sel_hi:[0,1,1]
	v_pk_add_f32 v[54:55], v[54:55], v[2:3]
	ds_read_b128 v[2:5], v80 offset:1536
	ds_read_b128 v[6:9], v80 offset:1552
	ds_read_b128 v[10:13], v80 offset:2048
	ds_read_b128 v[82:85], v80 offset:2064
	s_waitcnt lgkmcnt(3)
	v_mov_b32_e32 v87, v2
	s_waitcnt lgkmcnt(1)
	v_mov_b32_e32 v2, v11
	v_mov_b32_e32 v86, v10
	v_pk_mul_f32 v[2:3], v[70:71], v[2:3] op_sel_hi:[0,1]
	v_pk_fma_f32 v[2:3], v[64:65], v[86:87], v[2:3] op_sel_hi:[0,1,1]
	v_mov_b32_e32 v10, v12
	v_mov_b32_e32 v11, v4
	v_pk_fma_f32 v[2:3], v[62:63], v[10:11], v[2:3] op_sel_hi:[0,1,1]
	v_mov_b32_e32 v4, v13
	v_pk_fma_f32 v[2:3], v[68:69], v[4:5], v[2:3] op_sel_hi:[0,1,1]
	s_waitcnt lgkmcnt(0)
	v_mov_b32_e32 v4, v82
	v_mov_b32_e32 v5, v6
	v_pk_fma_f32 v[2:3], v[60:61], v[4:5], v[2:3] op_sel_hi:[0,1,1]
	v_mov_b32_e32 v6, v83
	v_pk_fma_f32 v[2:3], v[66:67], v[6:7], v[2:3] op_sel_hi:[0,1,1]
	v_mov_b32_e32 v4, v84
	v_mov_b32_e32 v5, v8
	v_pk_fma_f32 v[2:3], v[58:59], v[4:5], v[2:3] op_sel_hi:[0,1,1]
	v_mov_b32_e32 v8, v85
	v_pk_fma_f32 v[2:3], v[14:15], v[8:9], v[2:3] op_sel_hi:[0,1,1]
	v_pk_add_f32 v[52:53], v[52:53], v[2:3]
	ds_read_b128 v[2:5], v80 offset:2560
	ds_read_b128 v[6:9], v80 offset:2576
	ds_read_b128 v[10:13], v80 offset:3072
	ds_read_b128 v[82:85], v80 offset:3088
	s_waitcnt lgkmcnt(3)
	v_mov_b32_e32 v87, v2
	s_waitcnt lgkmcnt(1)
	v_mov_b32_e32 v2, v11
	v_mov_b32_e32 v86, v10
	v_pk_mul_f32 v[2:3], v[70:71], v[2:3] op_sel_hi:[0,1]
	v_pk_fma_f32 v[2:3], v[64:65], v[86:87], v[2:3] op_sel_hi:[0,1,1]
	v_mov_b32_e32 v10, v12
	v_mov_b32_e32 v11, v4
	v_pk_fma_f32 v[2:3], v[62:63], v[10:11], v[2:3] op_sel_hi:[0,1,1]
	v_mov_b32_e32 v4, v13
	v_pk_fma_f32 v[2:3], v[68:69], v[4:5], v[2:3] op_sel_hi:[0,1,1]
	s_waitcnt lgkmcnt(0)
	v_mov_b32_e32 v4, v82
	v_mov_b32_e32 v5, v6
	v_pk_fma_f32 v[2:3], v[60:61], v[4:5], v[2:3] op_sel_hi:[0,1,1]
	v_mov_b32_e32 v6, v83
	v_pk_fma_f32 v[2:3], v[66:67], v[6:7], v[2:3] op_sel_hi:[0,1,1]
	v_mov_b32_e32 v4, v84
	v_mov_b32_e32 v5, v8
	v_pk_fma_f32 v[2:3], v[58:59], v[4:5], v[2:3] op_sel_hi:[0,1,1]
	v_mov_b32_e32 v8, v85
	v_pk_fma_f32 v[2:3], v[14:15], v[8:9], v[2:3] op_sel_hi:[0,1,1]
	v_pk_add_f32 v[50:51], v[50:51], v[2:3]
	ds_read_b128 v[2:5], v80 offset:3584
	ds_read_b128 v[6:9], v80 offset:3600
	ds_read_b128 v[10:13], v80 offset:4096
	ds_read_b128 v[82:85], v80 offset:4112
	s_waitcnt lgkmcnt(3)
	v_mov_b32_e32 v87, v2
	s_waitcnt lgkmcnt(1)
	v_mov_b32_e32 v2, v11
	v_mov_b32_e32 v86, v10
	v_pk_mul_f32 v[2:3], v[70:71], v[2:3] op_sel_hi:[0,1]
	v_pk_fma_f32 v[2:3], v[64:65], v[86:87], v[2:3] op_sel_hi:[0,1,1]
	v_mov_b32_e32 v10, v12
	v_mov_b32_e32 v11, v4
	v_pk_fma_f32 v[2:3], v[62:63], v[10:11], v[2:3] op_sel_hi:[0,1,1]
	v_mov_b32_e32 v4, v13
	v_pk_fma_f32 v[2:3], v[68:69], v[4:5], v[2:3] op_sel_hi:[0,1,1]
	s_waitcnt lgkmcnt(0)
; __device__ __forceinline__ void phase0(const Params& p, char* smem) {
;     ...
; #pragma unroll
;           for (int b = 0; b < 33; ++b) {
;             float4 s0 = *(const float4*)(scw + b * 128 + k), s1 = *(const float4*)(scw + b * 128 + k + 4);
;             acc[b] += s0.x * wv[0] + s0.y * wv[1] + s0.z * wv[2] + s0.w * wv[3] + s1.x * wv[4] + s1.y * wv[5] + s1.z * wv[6] + s1.w * wv[7];
	v_mov_b32_e32 v4, v82
	v_mov_b32_e32 v5, v6
	v_pk_fma_f32 v[2:3], v[60:61], v[4:5], v[2:3] op_sel_hi:[0,1,1]
	v_mov_b32_e32 v6, v83
	v_pk_fma_f32 v[2:3], v[66:67], v[6:7], v[2:3] op_sel_hi:[0,1,1]
	v_mov_b32_e32 v4, v84
	v_mov_b32_e32 v5, v8
	v_pk_fma_f32 v[2:3], v[58:59], v[4:5], v[2:3] op_sel_hi:[0,1,1]
	v_mov_b32_e32 v8, v85
	v_pk_fma_f32 v[2:3], v[14:15], v[8:9], v[2:3] op_sel_hi:[0,1,1]
	v_pk_add_f32 v[48:49], v[48:49], v[2:3]
	ds_read_b128 v[2:5], v80 offset:4608
	ds_read_b128 v[6:9], v80 offset:4624
	ds_read_b128 v[10:13], v80 offset:5120
	ds_read_b128 v[82:85], v80 offset:5136
	s_waitcnt lgkmcnt(3)
	v_mov_b32_e32 v87, v2
	s_waitcnt lgkmcnt(1)
	v_mov_b32_e32 v2, v11
	v_mov_b32_e32 v86, v10
	v_pk_mul_f32 v[2:3], v[70:71], v[2:3] op_sel_hi:[0,1]
	v_pk_fma_f32 v[2:3], v[64:65], v[86:87], v[2:3] op_sel_hi:[0,1,1]
	v_mov_b32_e32 v10, v12
	v_mov_b32_e32 v11, v4
	v_pk_fma_f32 v[2:3], v[62:63], v[10:11], v[2:3] op_sel_hi:[0,1,1]
	v_mov_b32_e32 v4, v13
	v_pk_fma_f32 v[2:3], v[68:69], v[4:5], v[2:3] op_sel_hi:[0,1,1]
	s_waitcnt lgkmcnt(0)
	v_mov_b32_e32 v4, v82
	v_mov_b32_e32 v5, v6
	v_pk_fma_f32 v[2:3], v[60:61], v[4:5], v[2:3] op_sel_hi:[0,1,1]
	v_mov_b32_e32 v6, v83
	v_pk_fma_f32 v[2:3], v[66:67], v[6:7], v[2:3] op_sel_hi:[0,1,1]
	v_mov_b32_e32 v4, v84
	v_mov_b32_e32 v5, v8
	v_pk_fma_f32 v[2:3], v[58:59], v[4:5], v[2:3] op_sel_hi:[0,1,1]
	v_mov_b32_e32 v8, v85
	v_pk_fma_f32 v[2:3], v[14:15], v[8:9], v[2:3] op_sel_hi:[0,1,1]
	v_pk_add_f32 v[46:47], v[46:47], v[2:3]
	ds_read_b128 v[2:5], v80 offset:5632
	ds_read_b128 v[6:9], v80 offset:5648
	ds_read_b128 v[10:13], v80 offset:6144
	ds_read_b128 v[82:85], v80 offset:6160
	s_waitcnt lgkmcnt(3)
	v_mov_b32_e32 v87, v2
	s_waitcnt lgkmcnt(1)
	v_mov_b32_e32 v2, v11
	v_mov_b32_e32 v86, v10
	v_pk_mul_f32 v[2:3], v[70:71], v[2:3] op_sel_hi:[0,1]
	v_pk_fma_f32 v[2:3], v[64:65], v[86:87], v[2:3] op_sel_hi:[0,1,1]
	v_mov_b32_e32 v10, v12
	v_mov_b32_e32 v11, v4
	v_pk_fma_f32 v[2:3], v[62:63], v[10:11], v[2:3] op_sel_hi:[0,1,1]
	v_mov_b32_e32 v4, v13
	v_pk_fma_f32 v[2:3], v[68:69], v[4:5], v[2:3] op_sel_hi:[0,1,1]
	s_waitcnt lgkmcnt(0)
	v_mov_b32_e32 v4, v82
	v_mov_b32_e32 v5, v6
	v_pk_fma_f32 v[2:3], v[60:61], v[4:5], v[2:3] op_sel_hi:[0,1,1]
	v_mov_b32_e32 v6, v83
	v_pk_fma_f32 v[2:3], v[66:67], v[6:7], v[2:3] op_sel_hi:[0,1,1]
	v_mov_b32_e32 v4, v84
	v_mov_b32_e32 v5, v8
	v_pk_fma_f32 v[2:3], v[58:59], v[4:5], v[2:3] op_sel_hi:[0,1,1]
	v_mov_b32_e32 v8, v85
	v_pk_fma_f32 v[2:3], v[14:15], v[8:9], v[2:3] op_sel_hi:[0,1,1]
	v_pk_add_f32 v[44:45], v[44:45], v[2:3]
	ds_read_b128 v[2:5], v80 offset:6656
	ds_read_b128 v[6:9], v80 offset:6672
	ds_read_b128 v[10:13], v80 offset:7168
	ds_read_b128 v[82:85], v80 offset:7184
	s_waitcnt lgkmcnt(3)
	v_mov_b32_e32 v87, v2
	s_waitcnt lgkmcnt(1)
	v_mov_b32_e32 v2, v11
	v_mov_b32_e32 v86, v10
	v_pk_mul_f32 v[2:3], v[70:71], v[2:3] op_sel_hi:[0,1]
	v_pk_fma_f32 v[2:3], v[64:65], v[86:87], v[2:3] op_sel_hi:[0,1,1]
	v_mov_b32_e32 v10, v12
	v_mov_b32_e32 v11, v4
	v_pk_fma_f32 v[2:3], v[62:63], v[10:11], v[2:3] op_sel_hi:[0,1,1]
	v_mov_b32_e32 v4, v13
	v_pk_fma_f32 v[2:3], v[68:69], v[4:5], v[2:3] op_sel_hi:[0,1,1]
	s_waitcnt lgkmcnt(0)
	v_mov_b32_e32 v4, v82
	v_mov_b32_e32 v5, v6
	v_pk_fma_f32 v[2:3], v[60:61], v[4:5], v[2:3] op_sel_hi:[0,1,1]
	v_mov_b32_e32 v6, v83
	v_pk_fma_f32 v[2:3], v[66:67], v[6:7], v[2:3] op_sel_hi:[0,1,1]
	v_mov_b32_e32 v4, v84
	v_mov_b32_e32 v5, v8
	v_pk_fma_f32 v[2:3], v[58:59], v[4:5], v[2:3] op_sel_hi:[0,1,1]
	v_mov_b32_e32 v8, v85
	v_pk_fma_f32 v[2:3], v[14:15], v[8:9], v[2:3] op_sel_hi:[0,1,1]
	v_pk_add_f32 v[42:43], v[42:43], v[2:3]
	ds_read_b128 v[2:5], v80 offset:7680
	ds_read_b128 v[6:9], v80 offset:7696
	ds_read_b128 v[10:13], v80 offset:8192
	ds_read_b128 v[82:85], v80 offset:8208
	s_waitcnt lgkmcnt(3)
	v_mov_b32_e32 v87, v2
	s_waitcnt lgkmcnt(1)
	v_mov_b32_e32 v2, v11
	v_mov_b32_e32 v86, v10
	v_pk_mul_f32 v[2:3], v[70:71], v[2:3] op_sel_hi:[0,1]
	v_pk_fma_f32 v[2:3], v[64:65], v[86:87], v[2:3] op_sel_hi:[0,1,1]
	v_mov_b32_e32 v10, v12
	v_mov_b32_e32 v11, v4
	v_pk_fma_f32 v[2:3], v[62:63], v[10:11], v[2:3] op_sel_hi:[0,1,1]
	v_mov_b32_e32 v4, v13
	v_pk_fma_f32 v[2:3], v[68:69], v[4:5], v[2:3] op_sel_hi:[0,1,1]
	s_waitcnt lgkmcnt(0)
	v_mov_b32_e32 v4, v82
	v_mov_b32_e32 v5, v6
	v_pk_fma_f32 v[2:3], v[60:61], v[4:5], v[2:3] op_sel_hi:[0,1,1]
	v_mov_b32_e32 v6, v83
	v_pk_fma_f32 v[2:3], v[66:67], v[6:7], v[2:3] op_sel_hi:[0,1,1]
	v_mov_b32_e32 v4, v84
	v_mov_b32_e32 v5, v8
	v_pk_fma_f32 v[2:3], v[58:59], v[4:5], v[2:3] op_sel_hi:[0,1,1]
	v_mov_b32_e32 v8, v85
	v_pk_fma_f32 v[2:3], v[14:15], v[8:9], v[2:3] op_sel_hi:[0,1,1]
	v_pk_add_f32 v[40:41], v[40:41], v[2:3]
	ds_read_b128 v[2:5], v80 offset:8704
	ds_read_b128 v[6:9], v80 offset:8720
	ds_read_b128 v[10:13], v80 offset:9216
	ds_read_b128 v[82:85], v80 offset:9232
	s_waitcnt lgkmcnt(3)
	v_mov_b32_e32 v87, v2
	s_waitcnt lgkmcnt(1)
	v_mov_b32_e32 v2, v11
	v_mov_b32_e32 v86, v10
	v_pk_mul_f32 v[2:3], v[70:71], v[2:3] op_sel_hi:[0,1]
	v_pk_fma_f32 v[2:3], v[64:65], v[86:87], v[2:3] op_sel_hi:[0,1,1]
	v_mov_b32_e32 v10, v12
	v_mov_b32_e32 v11, v4
	v_pk_fma_f32 v[2:3], v[62:63], v[10:11], v[2:3] op_sel_hi:[0,1,1]
	v_mov_b32_e32 v4, v13
	v_pk_fma_f32 v[2:3], v[68:69], v[4:5], v[2:3] op_sel_hi:[0,1,1]
	s_waitcnt lgkmcnt(0)
	v_mov_b32_e32 v4, v82
	v_mov_b32_e32 v5, v6
	v_pk_fma_f32 v[2:3], v[60:61], v[4:5], v[2:3] op_sel_hi:[0,1,1]
	v_mov_b32_e32 v6, v83
	v_pk_fma_f32 v[2:3], v[66:67], v[6:7], v[2:3] op_sel_hi:[0,1,1]
	v_mov_b32_e32 v4, v84
	v_mov_b32_e32 v5, v8
	v_pk_fma_f32 v[2:3], v[58:59], v[4:5], v[2:3] op_sel_hi:[0,1,1]
	v_mov_b32_e32 v8, v85
	v_pk_fma_f32 v[2:3], v[14:15], v[8:9], v[2:3] op_sel_hi:[0,1,1]
	v_pk_add_f32 v[38:39], v[38:39], v[2:3]
	ds_read_b128 v[2:5], v80 offset:9728
	ds_read_b128 v[6:9], v80 offset:9744
	ds_read_b128 v[10:13], v80 offset:10240
	ds_read_b128 v[82:85], v80 offset:10256
	s_waitcnt lgkmcnt(3)
; __device__ __forceinline__ void phase0(const Params& p, char* smem) {
;     ...
; #pragma unroll
;           for (int b = 0; b < 33; ++b) {
;             float4 s0 = *(const float4*)(scw + b * 128 + k), s1 = *(const float4*)(scw + b * 128 + k + 4);
;             acc[b] += s0.x * wv[0] + s0.y * wv[1] + s0.z * wv[2] + s0.w * wv[3] + s1.x * wv[4] + s1.y * wv[5] + s1.z * wv[6] + s1.w * wv[7];
	v_mov_b32_e32 v87, v2
	s_waitcnt lgkmcnt(1)
	v_mov_b32_e32 v2, v11
	v_mov_b32_e32 v86, v10
	v_pk_mul_f32 v[2:3], v[70:71], v[2:3] op_sel_hi:[0,1]
	v_pk_fma_f32 v[2:3], v[64:65], v[86:87], v[2:3] op_sel_hi:[0,1,1]
	v_mov_b32_e32 v10, v12
	v_mov_b32_e32 v11, v4
	v_pk_fma_f32 v[2:3], v[62:63], v[10:11], v[2:3] op_sel_hi:[0,1,1]
	v_mov_b32_e32 v4, v13
	v_pk_fma_f32 v[2:3], v[68:69], v[4:5], v[2:3] op_sel_hi:[0,1,1]
	s_waitcnt lgkmcnt(0)
	v_mov_b32_e32 v4, v82
	v_mov_b32_e32 v5, v6
	v_pk_fma_f32 v[2:3], v[60:61], v[4:5], v[2:3] op_sel_hi:[0,1,1]
	v_mov_b32_e32 v6, v83
	v_pk_fma_f32 v[2:3], v[66:67], v[6:7], v[2:3] op_sel_hi:[0,1,1]
	v_mov_b32_e32 v4, v84
	v_mov_b32_e32 v5, v8
	v_pk_fma_f32 v[2:3], v[58:59], v[4:5], v[2:3] op_sel_hi:[0,1,1]
	v_mov_b32_e32 v8, v85
	v_pk_fma_f32 v[2:3], v[14:15], v[8:9], v[2:3] op_sel_hi:[0,1,1]
	v_pk_add_f32 v[36:37], v[36:37], v[2:3]
	ds_read_b128 v[2:5], v80 offset:10752
	ds_read_b128 v[6:9], v80 offset:10768
	ds_read_b128 v[10:13], v80 offset:11264
	ds_read_b128 v[82:85], v80 offset:11280
	s_waitcnt lgkmcnt(3)
	v_mov_b32_e32 v87, v2
	s_waitcnt lgkmcnt(1)
	v_mov_b32_e32 v2, v11
	v_mov_b32_e32 v86, v10
	v_pk_mul_f32 v[2:3], v[70:71], v[2:3] op_sel_hi:[0,1]
	v_pk_fma_f32 v[2:3], v[64:65], v[86:87], v[2:3] op_sel_hi:[0,1,1]
	v_mov_b32_e32 v10, v12
	v_mov_b32_e32 v11, v4
	v_pk_fma_f32 v[2:3], v[62:63], v[10:11], v[2:3] op_sel_hi:[0,1,1]
	v_mov_b32_e32 v4, v13
	v_pk_fma_f32 v[2:3], v[68:69], v[4:5], v[2:3] op_sel_hi:[0,1,1]
	s_waitcnt lgkmcnt(0)
	v_mov_b32_e32 v4, v82
	v_mov_b32_e32 v5, v6
	v_pk_fma_f32 v[2:3], v[60:61], v[4:5], v[2:3] op_sel_hi:[0,1,1]
	v_mov_b32_e32 v6, v83
	v_pk_fma_f32 v[2:3], v[66:67], v[6:7], v[2:3] op_sel_hi:[0,1,1]
	v_mov_b32_e32 v4, v84
	v_mov_b32_e32 v5, v8
	v_pk_fma_f32 v[2:3], v[58:59], v[4:5], v[2:3] op_sel_hi:[0,1,1]
	v_mov_b32_e32 v8, v85
	v_pk_fma_f32 v[2:3], v[14:15], v[8:9], v[2:3] op_sel_hi:[0,1,1]
	v_pk_add_f32 v[32:33], v[32:33], v[2:3]
	ds_read_b128 v[2:5], v80 offset:11776
	ds_read_b128 v[6:9], v80 offset:11792
	ds_read_b128 v[10:13], v80 offset:12288
	ds_read_b128 v[82:85], v80 offset:12304
	s_waitcnt lgkmcnt(3)
	v_mov_b32_e32 v87, v2
	s_waitcnt lgkmcnt(1)
	v_mov_b32_e32 v2, v11
	v_mov_b32_e32 v86, v10
	v_pk_mul_f32 v[2:3], v[70:71], v[2:3] op_sel_hi:[0,1]
	v_pk_fma_f32 v[2:3], v[64:65], v[86:87], v[2:3] op_sel_hi:[0,1,1]
	v_mov_b32_e32 v10, v12
	v_mov_b32_e32 v11, v4
	v_pk_fma_f32 v[2:3], v[62:63], v[10:11], v[2:3] op_sel_hi:[0,1,1]
	v_mov_b32_e32 v4, v13
	v_pk_fma_f32 v[2:3], v[68:69], v[4:5], v[2:3] op_sel_hi:[0,1,1]
	s_waitcnt lgkmcnt(0)
	v_mov_b32_e32 v4, v82
	v_mov_b32_e32 v5, v6
	v_pk_fma_f32 v[2:3], v[60:61], v[4:5], v[2:3] op_sel_hi:[0,1,1]
	v_mov_b32_e32 v6, v83
	v_pk_fma_f32 v[2:3], v[66:67], v[6:7], v[2:3] op_sel_hi:[0,1,1]
	v_mov_b32_e32 v4, v84
	v_mov_b32_e32 v5, v8
	v_pk_fma_f32 v[2:3], v[58:59], v[4:5], v[2:3] op_sel_hi:[0,1,1]
	v_mov_b32_e32 v8, v85
	v_pk_fma_f32 v[2:3], v[14:15], v[8:9], v[2:3] op_sel_hi:[0,1,1]
	v_pk_add_f32 v[30:31], v[30:31], v[2:3]
	ds_read_b128 v[2:5], v80 offset:12800
	ds_read_b128 v[6:9], v80 offset:12816
	ds_read_b128 v[10:13], v80 offset:13312
	ds_read_b128 v[82:85], v80 offset:13328
	s_waitcnt lgkmcnt(3)
	v_mov_b32_e32 v87, v2
	s_waitcnt lgkmcnt(1)
	v_mov_b32_e32 v2, v11
	v_mov_b32_e32 v86, v10
	v_pk_mul_f32 v[2:3], v[70:71], v[2:3] op_sel_hi:[0,1]
	v_pk_fma_f32 v[2:3], v[64:65], v[86:87], v[2:3] op_sel_hi:[0,1,1]
	v_mov_b32_e32 v10, v12
	v_mov_b32_e32 v11, v4
	v_pk_fma_f32 v[2:3], v[62:63], v[10:11], v[2:3] op_sel_hi:[0,1,1]
	v_mov_b32_e32 v4, v13
	v_pk_fma_f32 v[2:3], v[68:69], v[4:5], v[2:3] op_sel_hi:[0,1,1]
	s_waitcnt lgkmcnt(0)
	v_mov_b32_e32 v4, v82
	v_mov_b32_e32 v5, v6
	v_pk_fma_f32 v[2:3], v[60:61], v[4:5], v[2:3] op_sel_hi:[0,1,1]
	v_mov_b32_e32 v6, v83
	v_pk_fma_f32 v[2:3], v[66:67], v[6:7], v[2:3] op_sel_hi:[0,1,1]
	v_mov_b32_e32 v4, v84
	v_mov_b32_e32 v5, v8
	v_pk_fma_f32 v[2:3], v[58:59], v[4:5], v[2:3] op_sel_hi:[0,1,1]
	v_mov_b32_e32 v8, v85
	v_pk_fma_f32 v[2:3], v[14:15], v[8:9], v[2:3] op_sel_hi:[0,1,1]
	v_pk_add_f32 v[28:29], v[28:29], v[2:3]
	ds_read_b128 v[6:9], v80 offset:13824
	ds_read_b128 v[2:5], v80 offset:13840
	ds_read_b128 v[10:13], v80 offset:14336
	ds_read_b128 v[82:85], v80 offset:14352
	s_waitcnt lgkmcnt(3)
	v_mov_b32_e32 v87, v6
	s_waitcnt lgkmcnt(1)
; __device__ __forceinline__ void phase0(const Params& p, char* smem) {
;     ...
; #pragma unroll
;           for (int b = 0; b < 33; ++b) {
;             float4 s0 = *(const float4*)(scw + b * 128 + k), s1 = *(const float4*)(scw + b * 128 + k + 4);
;             acc[b] += s0.x * wv[0] + s0.y * wv[1] + s0.z * wv[2] + s0.w * wv[3] + s1.x * wv[4] + s1.y * wv[5] + s1.z * wv[6] + s1.w * wv[7];
;           }
;         }
;       }
;       __syncthreads();
;       float* red = (float*)hsm;
; #pragma unroll
;       for (int b = 0; b < 33; ++b) red[(w * 33 + b) * 64 + lane] = acc[b];
	v_mov_b32_e32 v6, v11
	v_mov_b32_e32 v86, v10
	v_pk_mul_f32 v[6:7], v[70:71], v[6:7] op_sel_hi:[0,1]
	v_pk_fma_f32 v[6:7], v[64:65], v[86:87], v[6:7] op_sel_hi:[0,1,1]
	v_mov_b32_e32 v10, v12
	v_mov_b32_e32 v11, v8
	v_pk_fma_f32 v[6:7], v[62:63], v[10:11], v[6:7] op_sel_hi:[0,1,1]
	v_mov_b32_e32 v8, v13
	v_pk_fma_f32 v[6:7], v[68:69], v[8:9], v[6:7] op_sel_hi:[0,1,1]
	s_waitcnt lgkmcnt(0)
	v_mov_b32_e32 v8, v82
	v_mov_b32_e32 v9, v2
	v_pk_fma_f32 v[6:7], v[60:61], v[8:9], v[6:7] op_sel_hi:[0,1,1]
	v_mov_b32_e32 v2, v83
	v_pk_fma_f32 v[2:3], v[66:67], v[2:3], v[6:7] op_sel_hi:[0,1,1]
	v_mov_b32_e32 v6, v84
	v_mov_b32_e32 v7, v4
	v_pk_fma_f32 v[2:3], v[58:59], v[6:7], v[2:3] op_sel_hi:[0,1,1]
	v_mov_b32_e32 v4, v85
	v_pk_fma_f32 v[2:3], v[14:15], v[4:5], v[2:3] op_sel_hi:[0,1,1]
	v_pk_add_f32 v[26:27], v[26:27], v[2:3]
	ds_read_b128 v[2:5], v80 offset:14848
	ds_read_b128 v[6:9], v80 offset:14864
	ds_read_b128 v[10:13], v80 offset:15360
	ds_read_b128 v[82:85], v80 offset:15376
	s_waitcnt lgkmcnt(3)
	v_mov_b32_e32 v87, v2
	s_waitcnt lgkmcnt(1)
	v_mov_b32_e32 v2, v11
	v_mov_b32_e32 v86, v10
	v_pk_mul_f32 v[2:3], v[70:71], v[2:3] op_sel_hi:[0,1]
	v_pk_fma_f32 v[2:3], v[64:65], v[86:87], v[2:3] op_sel_hi:[0,1,1]
	v_mov_b32_e32 v10, v12
	v_mov_b32_e32 v11, v4
	v_pk_fma_f32 v[2:3], v[62:63], v[10:11], v[2:3] op_sel_hi:[0,1,1]
	v_mov_b32_e32 v4, v13
	v_pk_fma_f32 v[2:3], v[68:69], v[4:5], v[2:3] op_sel_hi:[0,1,1]
	s_waitcnt lgkmcnt(0)
	v_mov_b32_e32 v4, v82
	v_mov_b32_e32 v5, v6
	v_pk_fma_f32 v[2:3], v[60:61], v[4:5], v[2:3] op_sel_hi:[0,1,1]
	v_mov_b32_e32 v6, v83
	v_pk_fma_f32 v[2:3], v[66:67], v[6:7], v[2:3] op_sel_hi:[0,1,1]
	v_mov_b32_e32 v4, v84
	v_mov_b32_e32 v5, v8
	v_pk_fma_f32 v[2:3], v[58:59], v[4:5], v[2:3] op_sel_hi:[0,1,1]
	v_mov_b32_e32 v8, v85
	v_pk_fma_f32 v[2:3], v[14:15], v[8:9], v[2:3] op_sel_hi:[0,1,1]
	v_pk_add_f32 v[24:25], v[24:25], v[2:3]
	ds_read_b128 v[2:5], v80 offset:15872
	ds_read_b128 v[6:9], v80 offset:15888
	ds_read_b128 v[10:13], v80 offset:16384
	ds_read_b128 v[82:85], v80 offset:16400
	v_add_u32_e32 v80, 32, v80
	s_waitcnt lgkmcnt(3)
	v_mov_b32_e32 v87, v2
	s_waitcnt lgkmcnt(1)
	v_mov_b32_e32 v2, v11
	v_mov_b32_e32 v86, v10
	v_pk_mul_f32 v[2:3], v[70:71], v[2:3] op_sel_hi:[0,1]
	v_pk_fma_f32 v[2:3], v[64:65], v[86:87], v[2:3] op_sel_hi:[0,1,1]
	v_mov_b32_e32 v10, v12
	v_mov_b32_e32 v11, v4
	v_pk_fma_f32 v[2:3], v[62:63], v[10:11], v[2:3] op_sel_hi:[0,1,1]
	v_mov_b32_e32 v4, v13
	v_pk_fma_f32 v[2:3], v[68:69], v[4:5], v[2:3] op_sel_hi:[0,1,1]
	s_waitcnt lgkmcnt(0)
	v_mov_b32_e32 v4, v82
	v_mov_b32_e32 v5, v6
	v_pk_fma_f32 v[2:3], v[60:61], v[4:5], v[2:3] op_sel_hi:[0,1,1]
	v_mov_b32_e32 v6, v83
	v_pk_fma_f32 v[2:3], v[66:67], v[6:7], v[2:3] op_sel_hi:[0,1,1]
	v_mov_b32_e32 v4, v84
	v_mov_b32_e32 v5, v8
	v_pk_fma_f32 v[2:3], v[58:59], v[4:5], v[2:3] op_sel_hi:[0,1,1]
	v_mov_b32_e32 v8, v85
	v_pk_fma_f32 v[2:3], v[14:15], v[8:9], v[2:3] op_sel_hi:[0,1,1]
	v_pk_add_f32 v[22:23], v[22:23], v[2:3]
	s_cbranch_scc1 .LBB0_1949
	s_movk_i32 s7, 0x80
	s_mov_b64 s[18:19], 0
	s_and_b64 vcc, exec, s[16:17]
	s_cbranch_vccz .LBB0_1942
	s_mul_i32 s7, s8, 0x1800
	s_add_i32 s10, s7, s6
	s_mul_i32 s8, s8, 33
	s_ashr_i32 s7, s6, 31
	s_ashr_i32 s9, s8, 31
	s_lshl_b64 s[6:7], s[6:7], 2
	v_lshl_add_u64 v[4:5], v[20:21], 0, s[8:9]
	v_mov_b64_e32 v[6:7], s[6:7]
	v_or_b32_e32 v2, s10, v16
	v_mad_u64_u32 v[6:7], s[6:7], v4, s63, v[6:7]
	v_ashrrev_i32_e32 v3, 31, v2
	v_mad_i32_i24 v7, v5, s63, v7
	v_lshl_add_u64 v[2:3], v[2:3], 2, s[20:21]
	v_lshl_add_u64 v[4:5], v[18:19], 0, v[6:7]
	s_mov_b64 s[6:7], 0
	v_mov_b32_e32 v6, v77
	v_mov_b32_e32 v7, v76
	v_mov_b32_e32 v8, v75
	s_barrier
	ds_write2st64_b32 v78, v79, v55 offset1:1
	ds_write2st64_b32 v78, v54, v53 offset0:2 offset1:3
	ds_write2st64_b32 v78, v52, v51 offset0:4 offset1:5
	ds_write2st64_b32 v78, v50, v49 offset0:6 offset1:7
	ds_write2st64_b32 v78, v48, v47 offset0:8 offset1:9
	ds_write2st64_b32 v78, v46, v45 offset0:10 offset1:11
	ds_write2st64_b32 v78, v44, v43 offset0:12 offset1:13
	ds_write2st64_b32 v78, v42, v41 offset0:14 offset1:15
	ds_write2st64_b32 v78, v40, v39 offset0:16 offset1:17
	ds_write2st64_b32 v78, v38, v37 offset0:18 offset1:19
	ds_write2st64_b32 v78, v36, v33 offset0:20 offset1:21
	ds_write2st64_b32 v78, v32, v31 offset0:22 offset1:23
	ds_write2st64_b32 v78, v30, v29 offset0:24 offset1:25
	ds_write2st64_b32 v78, v28, v27 offset0:26 offset1:27
	ds_write2st64_b32 v78, v26, v25 offset0:28 offset1:29
	ds_write2st64_b32 v78, v24, v23 offset0:30 offset1:31
	ds_write_b32 v78, v22 offset:8192
	s_waitcnt lgkmcnt(0)
	s_barrier
